# P0: silu(c) fill and adaLN GEMV issue all loads up front (one round trip each)
# speedup vs baseline: 1.0195x; 1.0052x over previous
.LBB0_5:
	global_load_dword v40, v[4:5], off
	v_lshl_add_u64 v[4:5], v[4:5], 0, s[4:5]
	global_load_dword v41, v[4:5], off
	v_lshl_add_u64 v[4:5], v[4:5], 0, s[4:5]
	global_load_dword v42, v[4:5], off
	v_lshl_add_u64 v[4:5], v[4:5], 0, s[4:5]
	global_load_dword v43, v[4:5], off
	v_lshl_add_u64 v[4:5], v[4:5], 0, s[4:5]
	global_load_dword v44, v[4:5], off
	v_lshl_add_u64 v[4:5], v[4:5], 0, s[4:5]
	global_load_dword v45, v[4:5], off
	v_lshl_add_u64 v[4:5], v[4:5], 0, s[4:5]
	global_load_dword v46, v[4:5], off
	v_lshl_add_u64 v[4:5], v[4:5], 0, s[4:5]
	global_load_dword v47, v[4:5], off
	v_lshl_add_u64 v[4:5], v[4:5], 0, s[4:5]
	global_load_dword v48, v[4:5], off
	v_lshl_add_u64 v[4:5], v[4:5], 0, s[4:5]
	global_load_dword v49, v[4:5], off
	v_lshl_add_u64 v[4:5], v[4:5], 0, s[4:5]
	global_load_dword v50, v[4:5], off
	v_lshl_add_u64 v[4:5], v[4:5], 0, s[4:5]
	global_load_dword v51, v[4:5], off
	v_lshl_add_u64 v[4:5], v[4:5], 0, s[4:5]
	global_load_dword v52, v[4:5], off
	v_lshl_add_u64 v[4:5], v[4:5], 0, s[4:5]
	global_load_dword v53, v[4:5], off
	v_lshl_add_u64 v[4:5], v[4:5], 0, s[4:5]
	global_load_dword v54, v[4:5], off
	v_lshl_add_u64 v[4:5], v[4:5], 0, s[4:5]
	global_load_dword v55, v[4:5], off
	v_ashrrev_i32_e32 v7, 10, v3
	v_add_u32_e32 v3, 0x200, v3
	v_and_b32_e32 v8, 0x1ff8, v1
	v_lshlrev_b32_e32 v8, 2, v8
	v_lshlrev_b32_e32 v7, 2, v7
	v_add3_u32 v7, 0, v8, v7
	v_add_u32_e32 v1, 0x1000, v1
	s_waitcnt vmcnt(15)
	v_mul_f32_e32 v9, 0xbfb8aa3b, v40
	v_exp_f32_e32 v9, v9
	s_nop 0
	v_add_f32_e32 v8, 1.0, v9
	v_div_scale_f32 v9, s[8:9], v8, v8, v40
	v_rcp_f32_e32 v10, v9
	v_div_scale_f32 v11, vcc, v40, v8, v40
	v_fma_f32 v12, -v9, v10, 1.0
	v_fmac_f32_e32 v10, v12, v10
	v_mul_f32_e32 v12, v11, v10
	v_fma_f32 v13, -v9, v12, v11
	v_fmac_f32_e32 v12, v13, v10
	v_fma_f32 v9, -v9, v12, v11
	v_div_fmas_f32 v9, v9, v10, v12
	v_div_fixup_f32 v40, v9, v8, v40
	ds_write_b32 v7, v40
	v_ashrrev_i32_e32 v7, 10, v3
	v_add_u32_e32 v3, 0x200, v3
	v_and_b32_e32 v8, 0x1ff8, v1
	v_lshlrev_b32_e32 v8, 2, v8
	v_lshlrev_b32_e32 v7, 2, v7
	v_add3_u32 v7, 0, v8, v7
	v_add_u32_e32 v1, 0x1000, v1
	s_waitcnt vmcnt(14)
	v_mul_f32_e32 v9, 0xbfb8aa3b, v41
	v_exp_f32_e32 v9, v9
	s_nop 0
	v_add_f32_e32 v8, 1.0, v9
	v_div_scale_f32 v9, s[8:9], v8, v8, v41
	v_rcp_f32_e32 v10, v9
	v_div_scale_f32 v11, vcc, v41, v8, v41
	v_fma_f32 v12, -v9, v10, 1.0
	v_fmac_f32_e32 v10, v12, v10
	v_mul_f32_e32 v12, v11, v10
	v_fma_f32 v13, -v9, v12, v11
	v_fmac_f32_e32 v12, v13, v10
	v_fma_f32 v9, -v9, v12, v11
	v_div_fmas_f32 v9, v9, v10, v12
	v_div_fixup_f32 v41, v9, v8, v41
	ds_write_b32 v7, v41
	v_ashrrev_i32_e32 v7, 10, v3
	v_add_u32_e32 v3, 0x200, v3
	v_and_b32_e32 v8, 0x1ff8, v1
	v_lshlrev_b32_e32 v8, 2, v8
	v_lshlrev_b32_e32 v7, 2, v7
	v_add3_u32 v7, 0, v8, v7
	v_add_u32_e32 v1, 0x1000, v1
	s_waitcnt vmcnt(13)
	v_mul_f32_e32 v9, 0xbfb8aa3b, v42
	v_exp_f32_e32 v9, v9
	s_nop 0
	v_add_f32_e32 v8, 1.0, v9
	v_div_scale_f32 v9, s[8:9], v8, v8, v42
	v_rcp_f32_e32 v10, v9
	v_div_scale_f32 v11, vcc, v42, v8, v42
	v_fma_f32 v12, -v9, v10, 1.0
	v_fmac_f32_e32 v10, v12, v10
	v_mul_f32_e32 v12, v11, v10
	v_fma_f32 v13, -v9, v12, v11
	v_fmac_f32_e32 v12, v13, v10
	v_fma_f32 v9, -v9, v12, v11
	v_div_fmas_f32 v9, v9, v10, v12
	v_div_fixup_f32 v42, v9, v8, v42
	ds_write_b32 v7, v42
	v_ashrrev_i32_e32 v7, 10, v3
	v_add_u32_e32 v3, 0x200, v3
	v_and_b32_e32 v8, 0x1ff8, v1
	v_lshlrev_b32_e32 v8, 2, v8
	v_lshlrev_b32_e32 v7, 2, v7
	v_add3_u32 v7, 0, v8, v7
	v_add_u32_e32 v1, 0x1000, v1
	s_waitcnt vmcnt(12)
	v_mul_f32_e32 v9, 0xbfb8aa3b, v43
	v_exp_f32_e32 v9, v9
	s_nop 0
	v_add_f32_e32 v8, 1.0, v9
	v_div_scale_f32 v9, s[8:9], v8, v8, v43
	v_rcp_f32_e32 v10, v9
	v_div_scale_f32 v11, vcc, v43, v8, v43
	v_fma_f32 v12, -v9, v10, 1.0
	v_fmac_f32_e32 v10, v12, v10
	v_mul_f32_e32 v12, v11, v10
	v_fma_f32 v13, -v9, v12, v11
	v_fmac_f32_e32 v12, v13, v10
	v_fma_f32 v9, -v9, v12, v11
	v_div_fmas_f32 v9, v9, v10, v12
	v_div_fixup_f32 v43, v9, v8, v43
	ds_write_b32 v7, v43
	v_ashrrev_i32_e32 v7, 10, v3
	v_add_u32_e32 v3, 0x200, v3
	v_and_b32_e32 v8, 0x1ff8, v1
	v_lshlrev_b32_e32 v8, 2, v8
	v_lshlrev_b32_e32 v7, 2, v7
	v_add3_u32 v7, 0, v8, v7
	v_add_u32_e32 v1, 0x1000, v1
	s_waitcnt vmcnt(11)
	v_mul_f32_e32 v9, 0xbfb8aa3b, v44
	v_exp_f32_e32 v9, v9
	s_nop 0
	v_add_f32_e32 v8, 1.0, v9
	v_div_scale_f32 v9, s[8:9], v8, v8, v44
	v_rcp_f32_e32 v10, v9
	v_div_scale_f32 v11, vcc, v44, v8, v44
	v_fma_f32 v12, -v9, v10, 1.0
	v_fmac_f32_e32 v10, v12, v10
	v_mul_f32_e32 v12, v11, v10
	v_fma_f32 v13, -v9, v12, v11
	v_fmac_f32_e32 v12, v13, v10
	v_fma_f32 v9, -v9, v12, v11
	v_div_fmas_f32 v9, v9, v10, v12
	v_div_fixup_f32 v44, v9, v8, v44
	ds_write_b32 v7, v44
	v_ashrrev_i32_e32 v7, 10, v3
	v_add_u32_e32 v3, 0x200, v3
	v_and_b32_e32 v8, 0x1ff8, v1
	v_lshlrev_b32_e32 v8, 2, v8
	v_lshlrev_b32_e32 v7, 2, v7
	v_add3_u32 v7, 0, v8, v7
	v_add_u32_e32 v1, 0x1000, v1
	s_waitcnt vmcnt(10)
	v_mul_f32_e32 v9, 0xbfb8aa3b, v45
	v_exp_f32_e32 v9, v9
	s_nop 0
	v_add_f32_e32 v8, 1.0, v9
	v_div_scale_f32 v9, s[8:9], v8, v8, v45
	v_rcp_f32_e32 v10, v9
	v_div_scale_f32 v11, vcc, v45, v8, v45
	v_fma_f32 v12, -v9, v10, 1.0
	v_fmac_f32_e32 v10, v12, v10
	v_mul_f32_e32 v12, v11, v10
	v_fma_f32 v13, -v9, v12, v11
	v_fmac_f32_e32 v12, v13, v10
	v_fma_f32 v9, -v9, v12, v11
	v_div_fmas_f32 v9, v9, v10, v12
	v_div_fixup_f32 v45, v9, v8, v45
	ds_write_b32 v7, v45
	v_ashrrev_i32_e32 v7, 10, v3
	v_add_u32_e32 v3, 0x200, v3
	v_and_b32_e32 v8, 0x1ff8, v1
	v_lshlrev_b32_e32 v8, 2, v8
	v_lshlrev_b32_e32 v7, 2, v7
	v_add3_u32 v7, 0, v8, v7
	v_add_u32_e32 v1, 0x1000, v1
	s_waitcnt vmcnt(9)
	v_mul_f32_e32 v9, 0xbfb8aa3b, v46
	v_exp_f32_e32 v9, v9
	s_nop 0
	v_add_f32_e32 v8, 1.0, v9
	v_div_scale_f32 v9, s[8:9], v8, v8, v46
	v_rcp_f32_e32 v10, v9
	v_div_scale_f32 v11, vcc, v46, v8, v46
	v_fma_f32 v12, -v9, v10, 1.0
	v_fmac_f32_e32 v10, v12, v10
	v_mul_f32_e32 v12, v11, v10
	v_fma_f32 v13, -v9, v12, v11
	v_fmac_f32_e32 v12, v13, v10
	v_fma_f32 v9, -v9, v12, v11
	v_div_fmas_f32 v9, v9, v10, v12
	v_div_fixup_f32 v46, v9, v8, v46
	ds_write_b32 v7, v46
	v_ashrrev_i32_e32 v7, 10, v3
	v_add_u32_e32 v3, 0x200, v3
	v_and_b32_e32 v8, 0x1ff8, v1
	v_lshlrev_b32_e32 v8, 2, v8
	v_lshlrev_b32_e32 v7, 2, v7
	v_add3_u32 v7, 0, v8, v7
	v_add_u32_e32 v1, 0x1000, v1
	s_waitcnt vmcnt(8)
	v_mul_f32_e32 v9, 0xbfb8aa3b, v47
	v_exp_f32_e32 v9, v9
	s_nop 0
	v_add_f32_e32 v8, 1.0, v9
	v_div_scale_f32 v9, s[8:9], v8, v8, v47
	v_rcp_f32_e32 v10, v9
	v_div_scale_f32 v11, vcc, v47, v8, v47
	v_fma_f32 v12, -v9, v10, 1.0
	v_fmac_f32_e32 v10, v12, v10
	v_mul_f32_e32 v12, v11, v10
	v_fma_f32 v13, -v9, v12, v11
	v_fmac_f32_e32 v12, v13, v10
	v_fma_f32 v9, -v9, v12, v11
	v_div_fmas_f32 v9, v9, v10, v12
	v_div_fixup_f32 v47, v9, v8, v47
	ds_write_b32 v7, v47
	v_ashrrev_i32_e32 v7, 10, v3
	v_add_u32_e32 v3, 0x200, v3
	v_and_b32_e32 v8, 0x1ff8, v1
	v_lshlrev_b32_e32 v8, 2, v8
	v_lshlrev_b32_e32 v7, 2, v7
	v_add3_u32 v7, 0, v8, v7
	v_add_u32_e32 v1, 0x1000, v1
	s_waitcnt vmcnt(7)
	v_mul_f32_e32 v9, 0xbfb8aa3b, v48
	v_exp_f32_e32 v9, v9
	s_nop 0
	v_add_f32_e32 v8, 1.0, v9
	v_div_scale_f32 v9, s[8:9], v8, v8, v48
	v_rcp_f32_e32 v10, v9
	v_div_scale_f32 v11, vcc, v48, v8, v48
	v_fma_f32 v12, -v9, v10, 1.0
	v_fmac_f32_e32 v10, v12, v10
	v_mul_f32_e32 v12, v11, v10
	v_fma_f32 v13, -v9, v12, v11
	v_fmac_f32_e32 v12, v13, v10
	v_fma_f32 v9, -v9, v12, v11
	v_div_fmas_f32 v9, v9, v10, v12
	v_div_fixup_f32 v48, v9, v8, v48
	ds_write_b32 v7, v48
	v_ashrrev_i32_e32 v7, 10, v3
	v_add_u32_e32 v3, 0x200, v3
	v_and_b32_e32 v8, 0x1ff8, v1
	v_lshlrev_b32_e32 v8, 2, v8
	v_lshlrev_b32_e32 v7, 2, v7
	v_add3_u32 v7, 0, v8, v7
	v_add_u32_e32 v1, 0x1000, v1
	s_waitcnt vmcnt(6)
	v_mul_f32_e32 v9, 0xbfb8aa3b, v49
	v_exp_f32_e32 v9, v9
	s_nop 0
	v_add_f32_e32 v8, 1.0, v9
	v_div_scale_f32 v9, s[8:9], v8, v8, v49
	v_rcp_f32_e32 v10, v9
	v_div_scale_f32 v11, vcc, v49, v8, v49
	v_fma_f32 v12, -v9, v10, 1.0
	v_fmac_f32_e32 v10, v12, v10
	v_mul_f32_e32 v12, v11, v10
	v_fma_f32 v13, -v9, v12, v11
	v_fmac_f32_e32 v12, v13, v10
	v_fma_f32 v9, -v9, v12, v11
	v_div_fmas_f32 v9, v9, v10, v12
	v_div_fixup_f32 v49, v9, v8, v49
	ds_write_b32 v7, v49
	v_ashrrev_i32_e32 v7, 10, v3
	v_add_u32_e32 v3, 0x200, v3
	v_and_b32_e32 v8, 0x1ff8, v1
	v_lshlrev_b32_e32 v8, 2, v8
	v_lshlrev_b32_e32 v7, 2, v7
	v_add3_u32 v7, 0, v8, v7
	v_add_u32_e32 v1, 0x1000, v1
	s_waitcnt vmcnt(5)
	v_mul_f32_e32 v9, 0xbfb8aa3b, v50
	v_exp_f32_e32 v9, v9
	s_nop 0
	v_add_f32_e32 v8, 1.0, v9
	v_div_scale_f32 v9, s[8:9], v8, v8, v50
	v_rcp_f32_e32 v10, v9
	v_div_scale_f32 v11, vcc, v50, v8, v50
	v_fma_f32 v12, -v9, v10, 1.0
	v_fmac_f32_e32 v10, v12, v10
	v_mul_f32_e32 v12, v11, v10
	v_fma_f32 v13, -v9, v12, v11
	v_fmac_f32_e32 v12, v13, v10
	v_fma_f32 v9, -v9, v12, v11
	v_div_fmas_f32 v9, v9, v10, v12
	v_div_fixup_f32 v50, v9, v8, v50
	ds_write_b32 v7, v50
	v_ashrrev_i32_e32 v7, 10, v3
	v_add_u32_e32 v3, 0x200, v3
	v_and_b32_e32 v8, 0x1ff8, v1
	v_lshlrev_b32_e32 v8, 2, v8
	v_lshlrev_b32_e32 v7, 2, v7
	v_add3_u32 v7, 0, v8, v7
	v_add_u32_e32 v1, 0x1000, v1
	s_waitcnt vmcnt(4)
	v_mul_f32_e32 v9, 0xbfb8aa3b, v51
	v_exp_f32_e32 v9, v9
	s_nop 0
	v_add_f32_e32 v8, 1.0, v9
	v_div_scale_f32 v9, s[8:9], v8, v8, v51
	v_rcp_f32_e32 v10, v9
	v_div_scale_f32 v11, vcc, v51, v8, v51
	v_fma_f32 v12, -v9, v10, 1.0
	v_fmac_f32_e32 v10, v12, v10
	v_mul_f32_e32 v12, v11, v10
	v_fma_f32 v13, -v9, v12, v11
	v_fmac_f32_e32 v12, v13, v10
	v_fma_f32 v9, -v9, v12, v11
	v_div_fmas_f32 v9, v9, v10, v12
	v_div_fixup_f32 v51, v9, v8, v51
	ds_write_b32 v7, v51
	v_ashrrev_i32_e32 v7, 10, v3
	v_add_u32_e32 v3, 0x200, v3
	v_and_b32_e32 v8, 0x1ff8, v1
	v_lshlrev_b32_e32 v8, 2, v8
	v_lshlrev_b32_e32 v7, 2, v7
	v_add3_u32 v7, 0, v8, v7
	v_add_u32_e32 v1, 0x1000, v1
	s_waitcnt vmcnt(3)
	v_mul_f32_e32 v9, 0xbfb8aa3b, v52
	v_exp_f32_e32 v9, v9
	s_nop 0
	v_add_f32_e32 v8, 1.0, v9
	v_div_scale_f32 v9, s[8:9], v8, v8, v52
	v_rcp_f32_e32 v10, v9
	v_div_scale_f32 v11, vcc, v52, v8, v52
	v_fma_f32 v12, -v9, v10, 1.0
	v_fmac_f32_e32 v10, v12, v10
	v_mul_f32_e32 v12, v11, v10
	v_fma_f32 v13, -v9, v12, v11
	v_fmac_f32_e32 v12, v13, v10
	v_fma_f32 v9, -v9, v12, v11
	v_div_fmas_f32 v9, v9, v10, v12
	v_div_fixup_f32 v52, v9, v8, v52
	ds_write_b32 v7, v52
	v_ashrrev_i32_e32 v7, 10, v3
	v_add_u32_e32 v3, 0x200, v3
	v_and_b32_e32 v8, 0x1ff8, v1
	v_lshlrev_b32_e32 v8, 2, v8
	v_lshlrev_b32_e32 v7, 2, v7
	v_add3_u32 v7, 0, v8, v7
	v_add_u32_e32 v1, 0x1000, v1
	s_waitcnt vmcnt(2)
	v_mul_f32_e32 v9, 0xbfb8aa3b, v53
	v_exp_f32_e32 v9, v9
	s_nop 0
	v_add_f32_e32 v8, 1.0, v9
	v_div_scale_f32 v9, s[8:9], v8, v8, v53
	v_rcp_f32_e32 v10, v9
	v_div_scale_f32 v11, vcc, v53, v8, v53
	v_fma_f32 v12, -v9, v10, 1.0
	v_fmac_f32_e32 v10, v12, v10
	v_mul_f32_e32 v12, v11, v10
	v_fma_f32 v13, -v9, v12, v11
	v_fmac_f32_e32 v12, v13, v10
	v_fma_f32 v9, -v9, v12, v11
	v_div_fmas_f32 v9, v9, v10, v12
	v_div_fixup_f32 v53, v9, v8, v53
	ds_write_b32 v7, v53
	v_ashrrev_i32_e32 v7, 10, v3
	v_add_u32_e32 v3, 0x200, v3
	v_and_b32_e32 v8, 0x1ff8, v1
	v_lshlrev_b32_e32 v8, 2, v8
	v_lshlrev_b32_e32 v7, 2, v7
	v_add3_u32 v7, 0, v8, v7
	v_add_u32_e32 v1, 0x1000, v1
	s_waitcnt vmcnt(1)
	v_mul_f32_e32 v9, 0xbfb8aa3b, v54
	v_exp_f32_e32 v9, v9
	s_nop 0
	v_add_f32_e32 v8, 1.0, v9
	v_div_scale_f32 v9, s[8:9], v8, v8, v54
	v_rcp_f32_e32 v10, v9
	v_div_scale_f32 v11, vcc, v54, v8, v54
	v_fma_f32 v12, -v9, v10, 1.0
	v_fmac_f32_e32 v10, v12, v10
	v_mul_f32_e32 v12, v11, v10
	v_fma_f32 v13, -v9, v12, v11
	v_fmac_f32_e32 v12, v13, v10
	v_fma_f32 v9, -v9, v12, v11
	v_div_fmas_f32 v9, v9, v10, v12
	v_div_fixup_f32 v54, v9, v8, v54
	ds_write_b32 v7, v54
	v_ashrrev_i32_e32 v7, 10, v3
	v_add_u32_e32 v3, 0x200, v3
	v_and_b32_e32 v8, 0x1ff8, v1
	v_lshlrev_b32_e32 v8, 2, v8
	v_lshlrev_b32_e32 v7, 2, v7
	v_add3_u32 v7, 0, v8, v7
	v_add_u32_e32 v1, 0x1000, v1
	s_waitcnt vmcnt(0)
	v_mul_f32_e32 v9, 0xbfb8aa3b, v55
	v_exp_f32_e32 v9, v9
	s_nop 0
	v_add_f32_e32 v8, 1.0, v9
	v_div_scale_f32 v9, s[8:9], v8, v8, v55
	v_rcp_f32_e32 v10, v9
	v_div_scale_f32 v11, vcc, v55, v8, v55
	v_fma_f32 v12, -v9, v10, 1.0
	v_fmac_f32_e32 v10, v12, v10
	v_mul_f32_e32 v12, v11, v10
	v_fma_f32 v13, -v9, v12, v11
	v_fmac_f32_e32 v12, v13, v10
	v_fma_f32 v9, -v9, v12, v11
	v_div_fmas_f32 v9, v9, v10, v12
	v_div_fixup_f32 v55, v9, v8, v55
	ds_write_b32 v7, v55

.LBB0_18:
	global_load_dword v92, v[14:15], off
	v_lshl_add_u64 v[26:27], v[14:15], 0, s[12:13]
	global_load_dword v94, v[26:27], off
	v_lshl_add_u64 v[26:27], v[26:27], 0, s[12:13]
	global_load_dword v96, v[26:27], off
	v_lshl_add_u64 v[26:27], v[26:27], 0, s[12:13]
	global_load_dword v98, v[26:27], off
	v_lshl_add_u64 v[26:27], v[26:27], 0, s[12:13]
	global_load_dword v100, v[26:27], off
	v_lshl_add_u64 v[26:27], v[26:27], 0, s[12:13]
	global_load_dword v102, v[26:27], off
	v_lshl_add_u64 v[26:27], v[26:27], 0, s[12:13]
	global_load_dword v104, v[26:27], off
	v_lshl_add_u64 v[26:27], v[26:27], 0, s[12:13]
	global_load_dword v106, v[26:27], off
	v_lshl_add_u64 v[14:15], v[14:15], 0, s[2:3]
	global_load_dword v108, v[14:15], off
	v_lshl_add_u64 v[26:27], v[14:15], 0, s[12:13]
	global_load_dword v110, v[26:27], off
	v_lshl_add_u64 v[26:27], v[26:27], 0, s[12:13]
	global_load_dword v112, v[26:27], off
	v_lshl_add_u64 v[26:27], v[26:27], 0, s[12:13]
	global_load_dword v114, v[26:27], off
	v_lshl_add_u64 v[26:27], v[26:27], 0, s[12:13]
	global_load_dword v116, v[26:27], off
	v_lshl_add_u64 v[26:27], v[26:27], 0, s[12:13]
	global_load_dword v118, v[26:27], off
	v_lshl_add_u64 v[26:27], v[26:27], 0, s[12:13]
	global_load_dword v120, v[26:27], off
	v_lshl_add_u64 v[26:27], v[26:27], 0, s[12:13]
	global_load_dword v122, v[26:27], off
	v_lshl_add_u64 v[14:15], v[14:15], 0, s[2:3]
	global_load_dword v124, v[14:15], off
	v_lshl_add_u64 v[26:27], v[14:15], 0, s[12:13]
	global_load_dword v126, v[26:27], off
	v_lshl_add_u64 v[26:27], v[26:27], 0, s[12:13]
	global_load_dword v128, v[26:27], off
	v_lshl_add_u64 v[26:27], v[26:27], 0, s[12:13]
	global_load_dword v130, v[26:27], off
	v_lshl_add_u64 v[26:27], v[26:27], 0, s[12:13]
	global_load_dword v132, v[26:27], off
	v_lshl_add_u64 v[26:27], v[26:27], 0, s[12:13]
	global_load_dword v134, v[26:27], off
	v_lshl_add_u64 v[26:27], v[26:27], 0, s[12:13]
	global_load_dword v136, v[26:27], off
	v_lshl_add_u64 v[26:27], v[26:27], 0, s[12:13]
	global_load_dword v138, v[26:27], off
	v_lshl_add_u64 v[14:15], v[14:15], 0, s[2:3]
	global_load_dword v140, v[14:15], off
	v_lshl_add_u64 v[26:27], v[14:15], 0, s[12:13]
	global_load_dword v142, v[26:27], off
	v_lshl_add_u64 v[26:27], v[26:27], 0, s[12:13]
	global_load_dword v144, v[26:27], off
	v_lshl_add_u64 v[26:27], v[26:27], 0, s[12:13]
	global_load_dword v146, v[26:27], off
	v_lshl_add_u64 v[26:27], v[26:27], 0, s[12:13]
	global_load_dword v148, v[26:27], off
	v_lshl_add_u64 v[26:27], v[26:27], 0, s[12:13]
	global_load_dword v150, v[26:27], off
	v_lshl_add_u64 v[26:27], v[26:27], 0, s[12:13]
	global_load_dword v152, v[26:27], off
	v_lshl_add_u64 v[26:27], v[26:27], 0, s[12:13]
	global_load_dword v154, v[26:27], off
	v_lshl_add_u64 v[14:15], v[14:15], 0, s[2:3]
	global_load_dword v156, v[14:15], off
	v_lshl_add_u64 v[26:27], v[14:15], 0, s[12:13]
	global_load_dword v158, v[26:27], off
	v_lshl_add_u64 v[26:27], v[26:27], 0, s[12:13]
	global_load_dword v160, v[26:27], off
	v_lshl_add_u64 v[26:27], v[26:27], 0, s[12:13]
	global_load_dword v162, v[26:27], off
	v_lshl_add_u64 v[26:27], v[26:27], 0, s[12:13]
	global_load_dword v164, v[26:27], off
	v_lshl_add_u64 v[26:27], v[26:27], 0, s[12:13]
	global_load_dword v166, v[26:27], off
	v_lshl_add_u64 v[26:27], v[26:27], 0, s[12:13]
	global_load_dword v168, v[26:27], off
	v_lshl_add_u64 v[26:27], v[26:27], 0, s[12:13]
	global_load_dword v170, v[26:27], off
	v_lshl_add_u64 v[14:15], v[14:15], 0, s[2:3]
	global_load_dword v172, v[14:15], off
	v_lshl_add_u64 v[26:27], v[14:15], 0, s[12:13]
	global_load_dword v174, v[26:27], off
	v_lshl_add_u64 v[26:27], v[26:27], 0, s[12:13]
	global_load_dword v176, v[26:27], off
	v_lshl_add_u64 v[26:27], v[26:27], 0, s[12:13]
	global_load_dword v178, v[26:27], off
	v_lshl_add_u64 v[26:27], v[26:27], 0, s[12:13]
	global_load_dword v180, v[26:27], off
	v_lshl_add_u64 v[26:27], v[26:27], 0, s[12:13]
	global_load_dword v182, v[26:27], off
	v_lshl_add_u64 v[26:27], v[26:27], 0, s[12:13]
	global_load_dword v184, v[26:27], off
	v_lshl_add_u64 v[26:27], v[26:27], 0, s[12:13]
	global_load_dword v186, v[26:27], off
	v_lshl_add_u64 v[14:15], v[14:15], 0, s[2:3]
	global_load_dword v188, v[14:15], off
	v_lshl_add_u64 v[26:27], v[14:15], 0, s[12:13]
	global_load_dword v190, v[26:27], off
	v_lshl_add_u64 v[26:27], v[26:27], 0, s[12:13]
	global_load_dword v192, v[26:27], off
	v_lshl_add_u64 v[26:27], v[26:27], 0, s[12:13]
	global_load_dword v194, v[26:27], off
	v_lshl_add_u64 v[26:27], v[26:27], 0, s[12:13]
	global_load_dword v196, v[26:27], off
	v_lshl_add_u64 v[26:27], v[26:27], 0, s[12:13]
	global_load_dword v198, v[26:27], off
	v_lshl_add_u64 v[26:27], v[26:27], 0, s[12:13]
	global_load_dword v200, v[26:27], off
	v_lshl_add_u64 v[26:27], v[26:27], 0, s[12:13]
	global_load_dword v202, v[26:27], off
	v_lshl_add_u64 v[14:15], v[14:15], 0, s[2:3]
	global_load_dword v204, v[14:15], off
	v_lshl_add_u64 v[26:27], v[14:15], 0, s[12:13]
	global_load_dword v206, v[26:27], off
	v_lshl_add_u64 v[26:27], v[26:27], 0, s[12:13]
	global_load_dword v208, v[26:27], off
	v_lshl_add_u64 v[26:27], v[26:27], 0, s[12:13]
	global_load_dword v210, v[26:27], off
	v_lshl_add_u64 v[26:27], v[26:27], 0, s[12:13]
	global_load_dword v212, v[26:27], off
	v_lshl_add_u64 v[26:27], v[26:27], 0, s[12:13]
	global_load_dword v214, v[26:27], off
	v_lshl_add_u64 v[26:27], v[26:27], 0, s[12:13]
	global_load_dword v216, v[26:27], off
	v_lshl_add_u64 v[26:27], v[26:27], 0, s[12:13]
	global_load_dword v218, v[26:27], off
	v_mov_b32_e32 v7, v5
	ds_read_b128 v[26:29], v7
	ds_read_b128 v[32:35], v7 offset:16
	ds_read_b128 v[36:39], v7 offset:32
	ds_read_b128 v[40:43], v7 offset:48
	ds_read_b128 v[44:47], v7 offset:64
	ds_read_b128 v[48:51], v7 offset:80
	ds_read_b128 v[52:55], v7 offset:96
	ds_read_b128 v[56:59], v7 offset:112
	ds_read_b128 v[60:63], v7 offset:128
	ds_read_b128 v[64:67], v7 offset:144
	ds_read_b128 v[68:71], v7 offset:160
	ds_read_b128 v[72:75], v7 offset:176
	ds_read_b128 v[76:79], v7 offset:192
	ds_read_b128 v[80:83], v7 offset:208
	ds_read_b128 v[84:87], v7 offset:224
	ds_read_b128 v[88:91], v7 offset:240
	s_waitcnt vmcnt(63) lgkmcnt(14)
	v_pk_fma_f32 v[16:17], v[26:27], v[92:93], v[16:17] op_sel_hi:[1,0,1]
	v_pk_fma_f32 v[18:19], v[28:29], v[92:93], v[18:19] op_sel_hi:[1,0,1]
	v_pk_fma_f32 v[22:23], v[32:33], v[92:93], v[22:23] op_sel_hi:[1,0,1]
	v_pk_fma_f32 v[20:21], v[34:35], v[92:93], v[20:21] op_sel_hi:[1,0,1]
	s_waitcnt vmcnt(62) lgkmcnt(13)
	v_pk_fma_f32 v[18:19], v[38:39], v[94:95], v[18:19] op_sel_hi:[1,0,1]
	v_pk_fma_f32 v[16:17], v[36:37], v[94:95], v[16:17] op_sel_hi:[1,0,1]
	s_waitcnt lgkmcnt(12)
	v_pk_fma_f32 v[20:21], v[42:43], v[94:95], v[20:21] op_sel_hi:[1,0,1]
	v_pk_fma_f32 v[22:23], v[40:41], v[94:95], v[22:23] op_sel_hi:[1,0,1]
	s_waitcnt vmcnt(61) lgkmcnt(11)
	v_pk_fma_f32 v[16:17], v[44:45], v[96:97], v[16:17] op_sel_hi:[1,0,1]
	v_pk_fma_f32 v[18:19], v[46:47], v[96:97], v[18:19] op_sel_hi:[1,0,1]
	s_waitcnt lgkmcnt(10)
	v_pk_fma_f32 v[22:23], v[48:49], v[96:97], v[22:23] op_sel_hi:[1,0,1]
	v_pk_fma_f32 v[20:21], v[50:51], v[96:97], v[20:21] op_sel_hi:[1,0,1]
	s_waitcnt vmcnt(60) lgkmcnt(9)
	v_pk_fma_f32 v[18:19], v[54:55], v[98:99], v[18:19] op_sel_hi:[1,0,1]
	v_pk_fma_f32 v[16:17], v[52:53], v[98:99], v[16:17] op_sel_hi:[1,0,1]
	s_waitcnt lgkmcnt(8)
	v_pk_fma_f32 v[20:21], v[58:59], v[98:99], v[20:21] op_sel_hi:[1,0,1]
	v_pk_fma_f32 v[22:23], v[56:57], v[98:99], v[22:23] op_sel_hi:[1,0,1]
	s_waitcnt vmcnt(59) lgkmcnt(7)
	v_pk_fma_f32 v[16:17], v[60:61], v[100:101], v[16:17] op_sel_hi:[1,0,1]
	v_pk_fma_f32 v[18:19], v[62:63], v[100:101], v[18:19] op_sel_hi:[1,0,1]
	s_waitcnt lgkmcnt(6)
	v_pk_fma_f32 v[22:23], v[64:65], v[100:101], v[22:23] op_sel_hi:[1,0,1]
	v_pk_fma_f32 v[20:21], v[66:67], v[100:101], v[20:21] op_sel_hi:[1,0,1]
	s_waitcnt vmcnt(58) lgkmcnt(5)
	v_pk_fma_f32 v[18:19], v[70:71], v[102:103], v[18:19] op_sel_hi:[1,0,1]
	v_pk_fma_f32 v[16:17], v[68:69], v[102:103], v[16:17] op_sel_hi:[1,0,1]
	s_waitcnt lgkmcnt(4)
	v_pk_fma_f32 v[20:21], v[74:75], v[102:103], v[20:21] op_sel_hi:[1,0,1]
	v_pk_fma_f32 v[22:23], v[72:73], v[102:103], v[22:23] op_sel_hi:[1,0,1]
	s_waitcnt vmcnt(57) lgkmcnt(3)
	v_pk_fma_f32 v[16:17], v[76:77], v[104:105], v[16:17] op_sel_hi:[1,0,1]
	v_pk_fma_f32 v[18:19], v[78:79], v[104:105], v[18:19] op_sel_hi:[1,0,1]
	s_waitcnt lgkmcnt(2)
	v_pk_fma_f32 v[22:23], v[80:81], v[104:105], v[22:23] op_sel_hi:[1,0,1]
	v_pk_fma_f32 v[20:21], v[82:83], v[104:105], v[20:21] op_sel_hi:[1,0,1]
	s_waitcnt vmcnt(56) lgkmcnt(1)
	v_pk_fma_f32 v[18:19], v[86:87], v[106:107], v[18:19] op_sel_hi:[1,0,1]
	v_pk_fma_f32 v[16:17], v[84:85], v[106:107], v[16:17] op_sel_hi:[1,0,1]
	s_waitcnt lgkmcnt(0)
	v_pk_fma_f32 v[20:21], v[90:91], v[106:107], v[20:21] op_sel_hi:[1,0,1]
	v_pk_fma_f32 v[22:23], v[88:89], v[106:107], v[22:23] op_sel_hi:[1,0,1]
	v_add_u32_e32 v7, 0x100, v5
	ds_read_b128 v[26:29], v7
	ds_read_b128 v[32:35], v7 offset:16
	ds_read_b128 v[36:39], v7 offset:32
	ds_read_b128 v[40:43], v7 offset:48
	ds_read_b128 v[44:47], v7 offset:64
	ds_read_b128 v[48:51], v7 offset:80
	ds_read_b128 v[52:55], v7 offset:96
	ds_read_b128 v[56:59], v7 offset:112
	ds_read_b128 v[60:63], v7 offset:128
	ds_read_b128 v[64:67], v7 offset:144
	ds_read_b128 v[68:71], v7 offset:160
	ds_read_b128 v[72:75], v7 offset:176
	ds_read_b128 v[76:79], v7 offset:192
	ds_read_b128 v[80:83], v7 offset:208
	ds_read_b128 v[84:87], v7 offset:224
	ds_read_b128 v[88:91], v7 offset:240
	s_waitcnt vmcnt(55) lgkmcnt(14)
	v_pk_fma_f32 v[16:17], v[26:27], v[108:109], v[16:17] op_sel_hi:[1,0,1]
	v_pk_fma_f32 v[18:19], v[28:29], v[108:109], v[18:19] op_sel_hi:[1,0,1]
	v_pk_fma_f32 v[22:23], v[32:33], v[108:109], v[22:23] op_sel_hi:[1,0,1]
	v_pk_fma_f32 v[20:21], v[34:35], v[108:109], v[20:21] op_sel_hi:[1,0,1]
	s_waitcnt vmcnt(54) lgkmcnt(13)
	v_pk_fma_f32 v[18:19], v[38:39], v[110:111], v[18:19] op_sel_hi:[1,0,1]
	v_pk_fma_f32 v[16:17], v[36:37], v[110:111], v[16:17] op_sel_hi:[1,0,1]
	s_waitcnt lgkmcnt(12)
	v_pk_fma_f32 v[20:21], v[42:43], v[110:111], v[20:21] op_sel_hi:[1,0,1]
	v_pk_fma_f32 v[22:23], v[40:41], v[110:111], v[22:23] op_sel_hi:[1,0,1]
	s_waitcnt vmcnt(53) lgkmcnt(11)
	v_pk_fma_f32 v[16:17], v[44:45], v[112:113], v[16:17] op_sel_hi:[1,0,1]
	v_pk_fma_f32 v[18:19], v[46:47], v[112:113], v[18:19] op_sel_hi:[1,0,1]
	s_waitcnt lgkmcnt(10)
	v_pk_fma_f32 v[22:23], v[48:49], v[112:113], v[22:23] op_sel_hi:[1,0,1]
	v_pk_fma_f32 v[20:21], v[50:51], v[112:113], v[20:21] op_sel_hi:[1,0,1]
	s_waitcnt vmcnt(52) lgkmcnt(9)
	v_pk_fma_f32 v[18:19], v[54:55], v[114:115], v[18:19] op_sel_hi:[1,0,1]
	v_pk_fma_f32 v[16:17], v[52:53], v[114:115], v[16:17] op_sel_hi:[1,0,1]
	s_waitcnt lgkmcnt(8)
	v_pk_fma_f32 v[20:21], v[58:59], v[114:115], v[20:21] op_sel_hi:[1,0,1]
	v_pk_fma_f32 v[22:23], v[56:57], v[114:115], v[22:23] op_sel_hi:[1,0,1]
	s_waitcnt vmcnt(51) lgkmcnt(7)
	v_pk_fma_f32 v[16:17], v[60:61], v[116:117], v[16:17] op_sel_hi:[1,0,1]
	v_pk_fma_f32 v[18:19], v[62:63], v[116:117], v[18:19] op_sel_hi:[1,0,1]
	s_waitcnt lgkmcnt(6)
	v_pk_fma_f32 v[22:23], v[64:65], v[116:117], v[22:23] op_sel_hi:[1,0,1]
	v_pk_fma_f32 v[20:21], v[66:67], v[116:117], v[20:21] op_sel_hi:[1,0,1]
	s_waitcnt vmcnt(50) lgkmcnt(5)
	v_pk_fma_f32 v[18:19], v[70:71], v[118:119], v[18:19] op_sel_hi:[1,0,1]
	v_pk_fma_f32 v[16:17], v[68:69], v[118:119], v[16:17] op_sel_hi:[1,0,1]
	s_waitcnt lgkmcnt(4)
	v_pk_fma_f32 v[20:21], v[74:75], v[118:119], v[20:21] op_sel_hi:[1,0,1]
	v_pk_fma_f32 v[22:23], v[72:73], v[118:119], v[22:23] op_sel_hi:[1,0,1]
	s_waitcnt vmcnt(49) lgkmcnt(3)
	v_pk_fma_f32 v[16:17], v[76:77], v[120:121], v[16:17] op_sel_hi:[1,0,1]
	v_pk_fma_f32 v[18:19], v[78:79], v[120:121], v[18:19] op_sel_hi:[1,0,1]
	s_waitcnt lgkmcnt(2)
	v_pk_fma_f32 v[22:23], v[80:81], v[120:121], v[22:23] op_sel_hi:[1,0,1]
	v_pk_fma_f32 v[20:21], v[82:83], v[120:121], v[20:21] op_sel_hi:[1,0,1]
	s_waitcnt vmcnt(48) lgkmcnt(1)
	v_pk_fma_f32 v[18:19], v[86:87], v[122:123], v[18:19] op_sel_hi:[1,0,1]
	v_pk_fma_f32 v[16:17], v[84:85], v[122:123], v[16:17] op_sel_hi:[1,0,1]
	s_waitcnt lgkmcnt(0)
	v_pk_fma_f32 v[20:21], v[90:91], v[122:123], v[20:21] op_sel_hi:[1,0,1]
	v_pk_fma_f32 v[22:23], v[88:89], v[122:123], v[22:23] op_sel_hi:[1,0,1]
	v_add_u32_e32 v7, 0x200, v5
	ds_read_b128 v[26:29], v7
	ds_read_b128 v[32:35], v7 offset:16
	ds_read_b128 v[36:39], v7 offset:32
	ds_read_b128 v[40:43], v7 offset:48
	ds_read_b128 v[44:47], v7 offset:64
	ds_read_b128 v[48:51], v7 offset:80
	ds_read_b128 v[52:55], v7 offset:96
	ds_read_b128 v[56:59], v7 offset:112
	ds_read_b128 v[60:63], v7 offset:128
	ds_read_b128 v[64:67], v7 offset:144
	ds_read_b128 v[68:71], v7 offset:160
	ds_read_b128 v[72:75], v7 offset:176
	ds_read_b128 v[76:79], v7 offset:192
	ds_read_b128 v[80:83], v7 offset:208
	ds_read_b128 v[84:87], v7 offset:224
	ds_read_b128 v[88:91], v7 offset:240
	s_waitcnt vmcnt(47) lgkmcnt(14)
	v_pk_fma_f32 v[16:17], v[26:27], v[124:125], v[16:17] op_sel_hi:[1,0,1]
	v_pk_fma_f32 v[18:19], v[28:29], v[124:125], v[18:19] op_sel_hi:[1,0,1]
	v_pk_fma_f32 v[22:23], v[32:33], v[124:125], v[22:23] op_sel_hi:[1,0,1]
	v_pk_fma_f32 v[20:21], v[34:35], v[124:125], v[20:21] op_sel_hi:[1,0,1]
	s_waitcnt vmcnt(46) lgkmcnt(13)
	v_pk_fma_f32 v[18:19], v[38:39], v[126:127], v[18:19] op_sel_hi:[1,0,1]
	v_pk_fma_f32 v[16:17], v[36:37], v[126:127], v[16:17] op_sel_hi:[1,0,1]
	s_waitcnt lgkmcnt(12)
	v_pk_fma_f32 v[20:21], v[42:43], v[126:127], v[20:21] op_sel_hi:[1,0,1]
	v_pk_fma_f32 v[22:23], v[40:41], v[126:127], v[22:23] op_sel_hi:[1,0,1]
	s_waitcnt vmcnt(45) lgkmcnt(11)
	v_pk_fma_f32 v[16:17], v[44:45], v[128:129], v[16:17] op_sel_hi:[1,0,1]
	v_pk_fma_f32 v[18:19], v[46:47], v[128:129], v[18:19] op_sel_hi:[1,0,1]
	s_waitcnt lgkmcnt(10)
	v_pk_fma_f32 v[22:23], v[48:49], v[128:129], v[22:23] op_sel_hi:[1,0,1]
	v_pk_fma_f32 v[20:21], v[50:51], v[128:129], v[20:21] op_sel_hi:[1,0,1]
	s_waitcnt vmcnt(44) lgkmcnt(9)
	v_pk_fma_f32 v[18:19], v[54:55], v[130:131], v[18:19] op_sel_hi:[1,0,1]
	v_pk_fma_f32 v[16:17], v[52:53], v[130:131], v[16:17] op_sel_hi:[1,0,1]
	s_waitcnt lgkmcnt(8)
	v_pk_fma_f32 v[20:21], v[58:59], v[130:131], v[20:21] op_sel_hi:[1,0,1]
	v_pk_fma_f32 v[22:23], v[56:57], v[130:131], v[22:23] op_sel_hi:[1,0,1]
	s_waitcnt vmcnt(43) lgkmcnt(7)
	v_pk_fma_f32 v[16:17], v[60:61], v[132:133], v[16:17] op_sel_hi:[1,0,1]
	v_pk_fma_f32 v[18:19], v[62:63], v[132:133], v[18:19] op_sel_hi:[1,0,1]
	s_waitcnt lgkmcnt(6)
	v_pk_fma_f32 v[22:23], v[64:65], v[132:133], v[22:23] op_sel_hi:[1,0,1]
	v_pk_fma_f32 v[20:21], v[66:67], v[132:133], v[20:21] op_sel_hi:[1,0,1]
	s_waitcnt vmcnt(42) lgkmcnt(5)
	v_pk_fma_f32 v[18:19], v[70:71], v[134:135], v[18:19] op_sel_hi:[1,0,1]
	v_pk_fma_f32 v[16:17], v[68:69], v[134:135], v[16:17] op_sel_hi:[1,0,1]
	s_waitcnt lgkmcnt(4)
	v_pk_fma_f32 v[20:21], v[74:75], v[134:135], v[20:21] op_sel_hi:[1,0,1]
	v_pk_fma_f32 v[22:23], v[72:73], v[134:135], v[22:23] op_sel_hi:[1,0,1]
	s_waitcnt vmcnt(41) lgkmcnt(3)
	v_pk_fma_f32 v[16:17], v[76:77], v[136:137], v[16:17] op_sel_hi:[1,0,1]
	v_pk_fma_f32 v[18:19], v[78:79], v[136:137], v[18:19] op_sel_hi:[1,0,1]
	s_waitcnt lgkmcnt(2)
	v_pk_fma_f32 v[22:23], v[80:81], v[136:137], v[22:23] op_sel_hi:[1,0,1]
	v_pk_fma_f32 v[20:21], v[82:83], v[136:137], v[20:21] op_sel_hi:[1,0,1]
	s_waitcnt vmcnt(40) lgkmcnt(1)
	v_pk_fma_f32 v[18:19], v[86:87], v[138:139], v[18:19] op_sel_hi:[1,0,1]
	v_pk_fma_f32 v[16:17], v[84:85], v[138:139], v[16:17] op_sel_hi:[1,0,1]
	s_waitcnt lgkmcnt(0)
	v_pk_fma_f32 v[20:21], v[90:91], v[138:139], v[20:21] op_sel_hi:[1,0,1]
	v_pk_fma_f32 v[22:23], v[88:89], v[138:139], v[22:23] op_sel_hi:[1,0,1]
	v_add_u32_e32 v7, 0x300, v5
	ds_read_b128 v[26:29], v7
	ds_read_b128 v[32:35], v7 offset:16
	ds_read_b128 v[36:39], v7 offset:32
	ds_read_b128 v[40:43], v7 offset:48
	ds_read_b128 v[44:47], v7 offset:64
	ds_read_b128 v[48:51], v7 offset:80
	ds_read_b128 v[52:55], v7 offset:96
	ds_read_b128 v[56:59], v7 offset:112
	ds_read_b128 v[60:63], v7 offset:128
	ds_read_b128 v[64:67], v7 offset:144
	ds_read_b128 v[68:71], v7 offset:160
	ds_read_b128 v[72:75], v7 offset:176
	ds_read_b128 v[76:79], v7 offset:192
	ds_read_b128 v[80:83], v7 offset:208
	ds_read_b128 v[84:87], v7 offset:224
	ds_read_b128 v[88:91], v7 offset:240
	s_waitcnt vmcnt(39) lgkmcnt(14)
	v_pk_fma_f32 v[16:17], v[26:27], v[140:141], v[16:17] op_sel_hi:[1,0,1]
	v_pk_fma_f32 v[18:19], v[28:29], v[140:141], v[18:19] op_sel_hi:[1,0,1]
	v_pk_fma_f32 v[22:23], v[32:33], v[140:141], v[22:23] op_sel_hi:[1,0,1]
	v_pk_fma_f32 v[20:21], v[34:35], v[140:141], v[20:21] op_sel_hi:[1,0,1]
	s_waitcnt vmcnt(38) lgkmcnt(13)
	v_pk_fma_f32 v[18:19], v[38:39], v[142:143], v[18:19] op_sel_hi:[1,0,1]
	v_pk_fma_f32 v[16:17], v[36:37], v[142:143], v[16:17] op_sel_hi:[1,0,1]
	s_waitcnt lgkmcnt(12)
	v_pk_fma_f32 v[20:21], v[42:43], v[142:143], v[20:21] op_sel_hi:[1,0,1]
	v_pk_fma_f32 v[22:23], v[40:41], v[142:143], v[22:23] op_sel_hi:[1,0,1]
	s_waitcnt vmcnt(37) lgkmcnt(11)
	v_pk_fma_f32 v[16:17], v[44:45], v[144:145], v[16:17] op_sel_hi:[1,0,1]
	v_pk_fma_f32 v[18:19], v[46:47], v[144:145], v[18:19] op_sel_hi:[1,0,1]
	s_waitcnt lgkmcnt(10)
	v_pk_fma_f32 v[22:23], v[48:49], v[144:145], v[22:23] op_sel_hi:[1,0,1]
	v_pk_fma_f32 v[20:21], v[50:51], v[144:145], v[20:21] op_sel_hi:[1,0,1]
	s_waitcnt vmcnt(36) lgkmcnt(9)
	v_pk_fma_f32 v[18:19], v[54:55], v[146:147], v[18:19] op_sel_hi:[1,0,1]
	v_pk_fma_f32 v[16:17], v[52:53], v[146:147], v[16:17] op_sel_hi:[1,0,1]
	s_waitcnt lgkmcnt(8)
	v_pk_fma_f32 v[20:21], v[58:59], v[146:147], v[20:21] op_sel_hi:[1,0,1]
	v_pk_fma_f32 v[22:23], v[56:57], v[146:147], v[22:23] op_sel_hi:[1,0,1]
	s_waitcnt vmcnt(35) lgkmcnt(7)
	v_pk_fma_f32 v[16:17], v[60:61], v[148:149], v[16:17] op_sel_hi:[1,0,1]
	v_pk_fma_f32 v[18:19], v[62:63], v[148:149], v[18:19] op_sel_hi:[1,0,1]
	s_waitcnt lgkmcnt(6)
	v_pk_fma_f32 v[22:23], v[64:65], v[148:149], v[22:23] op_sel_hi:[1,0,1]
	v_pk_fma_f32 v[20:21], v[66:67], v[148:149], v[20:21] op_sel_hi:[1,0,1]
	s_waitcnt vmcnt(34) lgkmcnt(5)
	v_pk_fma_f32 v[18:19], v[70:71], v[150:151], v[18:19] op_sel_hi:[1,0,1]
	v_pk_fma_f32 v[16:17], v[68:69], v[150:151], v[16:17] op_sel_hi:[1,0,1]
	s_waitcnt lgkmcnt(4)
	v_pk_fma_f32 v[20:21], v[74:75], v[150:151], v[20:21] op_sel_hi:[1,0,1]
	v_pk_fma_f32 v[22:23], v[72:73], v[150:151], v[22:23] op_sel_hi:[1,0,1]
	s_waitcnt vmcnt(33) lgkmcnt(3)
	v_pk_fma_f32 v[16:17], v[76:77], v[152:153], v[16:17] op_sel_hi:[1,0,1]
	v_pk_fma_f32 v[18:19], v[78:79], v[152:153], v[18:19] op_sel_hi:[1,0,1]
	s_waitcnt lgkmcnt(2)
	v_pk_fma_f32 v[22:23], v[80:81], v[152:153], v[22:23] op_sel_hi:[1,0,1]
	v_pk_fma_f32 v[20:21], v[82:83], v[152:153], v[20:21] op_sel_hi:[1,0,1]
	s_waitcnt vmcnt(32) lgkmcnt(1)
	v_pk_fma_f32 v[18:19], v[86:87], v[154:155], v[18:19] op_sel_hi:[1,0,1]
	v_pk_fma_f32 v[16:17], v[84:85], v[154:155], v[16:17] op_sel_hi:[1,0,1]
	s_waitcnt lgkmcnt(0)
	v_pk_fma_f32 v[20:21], v[90:91], v[154:155], v[20:21] op_sel_hi:[1,0,1]
	v_pk_fma_f32 v[22:23], v[88:89], v[154:155], v[22:23] op_sel_hi:[1,0,1]
	v_add_u32_e32 v7, 0x400, v5
	ds_read_b128 v[26:29], v7
	ds_read_b128 v[32:35], v7 offset:16
	ds_read_b128 v[36:39], v7 offset:32
	ds_read_b128 v[40:43], v7 offset:48
	ds_read_b128 v[44:47], v7 offset:64
	ds_read_b128 v[48:51], v7 offset:80
	ds_read_b128 v[52:55], v7 offset:96
	ds_read_b128 v[56:59], v7 offset:112
	ds_read_b128 v[60:63], v7 offset:128
	ds_read_b128 v[64:67], v7 offset:144
	ds_read_b128 v[68:71], v7 offset:160
	ds_read_b128 v[72:75], v7 offset:176
	ds_read_b128 v[76:79], v7 offset:192
	ds_read_b128 v[80:83], v7 offset:208
	ds_read_b128 v[84:87], v7 offset:224
	ds_read_b128 v[88:91], v7 offset:240
	s_waitcnt vmcnt(31) lgkmcnt(14)
	v_pk_fma_f32 v[16:17], v[26:27], v[156:157], v[16:17] op_sel_hi:[1,0,1]
	v_pk_fma_f32 v[18:19], v[28:29], v[156:157], v[18:19] op_sel_hi:[1,0,1]
	v_pk_fma_f32 v[22:23], v[32:33], v[156:157], v[22:23] op_sel_hi:[1,0,1]
	v_pk_fma_f32 v[20:21], v[34:35], v[156:157], v[20:21] op_sel_hi:[1,0,1]
	s_waitcnt vmcnt(30) lgkmcnt(13)
	v_pk_fma_f32 v[18:19], v[38:39], v[158:159], v[18:19] op_sel_hi:[1,0,1]
	v_pk_fma_f32 v[16:17], v[36:37], v[158:159], v[16:17] op_sel_hi:[1,0,1]
	s_waitcnt lgkmcnt(12)
	v_pk_fma_f32 v[20:21], v[42:43], v[158:159], v[20:21] op_sel_hi:[1,0,1]
	v_pk_fma_f32 v[22:23], v[40:41], v[158:159], v[22:23] op_sel_hi:[1,0,1]
	s_waitcnt vmcnt(29) lgkmcnt(11)
	v_pk_fma_f32 v[16:17], v[44:45], v[160:161], v[16:17] op_sel_hi:[1,0,1]
	v_pk_fma_f32 v[18:19], v[46:47], v[160:161], v[18:19] op_sel_hi:[1,0,1]
	s_waitcnt lgkmcnt(10)
	v_pk_fma_f32 v[22:23], v[48:49], v[160:161], v[22:23] op_sel_hi:[1,0,1]
	v_pk_fma_f32 v[20:21], v[50:51], v[160:161], v[20:21] op_sel_hi:[1,0,1]
	s_waitcnt vmcnt(28) lgkmcnt(9)
	v_pk_fma_f32 v[18:19], v[54:55], v[162:163], v[18:19] op_sel_hi:[1,0,1]
	v_pk_fma_f32 v[16:17], v[52:53], v[162:163], v[16:17] op_sel_hi:[1,0,1]
	s_waitcnt lgkmcnt(8)
	v_pk_fma_f32 v[20:21], v[58:59], v[162:163], v[20:21] op_sel_hi:[1,0,1]
	v_pk_fma_f32 v[22:23], v[56:57], v[162:163], v[22:23] op_sel_hi:[1,0,1]
	s_waitcnt vmcnt(27) lgkmcnt(7)
	v_pk_fma_f32 v[16:17], v[60:61], v[164:165], v[16:17] op_sel_hi:[1,0,1]
	v_pk_fma_f32 v[18:19], v[62:63], v[164:165], v[18:19] op_sel_hi:[1,0,1]
	s_waitcnt lgkmcnt(6)
	v_pk_fma_f32 v[22:23], v[64:65], v[164:165], v[22:23] op_sel_hi:[1,0,1]
	v_pk_fma_f32 v[20:21], v[66:67], v[164:165], v[20:21] op_sel_hi:[1,0,1]
	s_waitcnt vmcnt(26) lgkmcnt(5)
	v_pk_fma_f32 v[18:19], v[70:71], v[166:167], v[18:19] op_sel_hi:[1,0,1]
	v_pk_fma_f32 v[16:17], v[68:69], v[166:167], v[16:17] op_sel_hi:[1,0,1]
	s_waitcnt lgkmcnt(4)
	v_pk_fma_f32 v[20:21], v[74:75], v[166:167], v[20:21] op_sel_hi:[1,0,1]
	v_pk_fma_f32 v[22:23], v[72:73], v[166:167], v[22:23] op_sel_hi:[1,0,1]
	s_waitcnt vmcnt(25) lgkmcnt(3)
	v_pk_fma_f32 v[16:17], v[76:77], v[168:169], v[16:17] op_sel_hi:[1,0,1]
	v_pk_fma_f32 v[18:19], v[78:79], v[168:169], v[18:19] op_sel_hi:[1,0,1]
	s_waitcnt lgkmcnt(2)
	v_pk_fma_f32 v[22:23], v[80:81], v[168:169], v[22:23] op_sel_hi:[1,0,1]
	v_pk_fma_f32 v[20:21], v[82:83], v[168:169], v[20:21] op_sel_hi:[1,0,1]
	s_waitcnt vmcnt(24) lgkmcnt(1)
	v_pk_fma_f32 v[18:19], v[86:87], v[170:171], v[18:19] op_sel_hi:[1,0,1]
	v_pk_fma_f32 v[16:17], v[84:85], v[170:171], v[16:17] op_sel_hi:[1,0,1]
	s_waitcnt lgkmcnt(0)
	v_pk_fma_f32 v[20:21], v[90:91], v[170:171], v[20:21] op_sel_hi:[1,0,1]
	v_pk_fma_f32 v[22:23], v[88:89], v[170:171], v[22:23] op_sel_hi:[1,0,1]
	v_add_u32_e32 v7, 0x500, v5
	ds_read_b128 v[26:29], v7
	ds_read_b128 v[32:35], v7 offset:16
	ds_read_b128 v[36:39], v7 offset:32
	ds_read_b128 v[40:43], v7 offset:48
	ds_read_b128 v[44:47], v7 offset:64
	ds_read_b128 v[48:51], v7 offset:80
	ds_read_b128 v[52:55], v7 offset:96
	ds_read_b128 v[56:59], v7 offset:112
	ds_read_b128 v[60:63], v7 offset:128
	ds_read_b128 v[64:67], v7 offset:144
	ds_read_b128 v[68:71], v7 offset:160
	ds_read_b128 v[72:75], v7 offset:176
	ds_read_b128 v[76:79], v7 offset:192
	ds_read_b128 v[80:83], v7 offset:208
	ds_read_b128 v[84:87], v7 offset:224
	ds_read_b128 v[88:91], v7 offset:240
	s_waitcnt vmcnt(23) lgkmcnt(14)
	v_pk_fma_f32 v[16:17], v[26:27], v[172:173], v[16:17] op_sel_hi:[1,0,1]
	v_pk_fma_f32 v[18:19], v[28:29], v[172:173], v[18:19] op_sel_hi:[1,0,1]
	v_pk_fma_f32 v[22:23], v[32:33], v[172:173], v[22:23] op_sel_hi:[1,0,1]
	v_pk_fma_f32 v[20:21], v[34:35], v[172:173], v[20:21] op_sel_hi:[1,0,1]
	s_waitcnt vmcnt(22) lgkmcnt(13)
	v_pk_fma_f32 v[18:19], v[38:39], v[174:175], v[18:19] op_sel_hi:[1,0,1]
	v_pk_fma_f32 v[16:17], v[36:37], v[174:175], v[16:17] op_sel_hi:[1,0,1]
	s_waitcnt lgkmcnt(12)
	v_pk_fma_f32 v[20:21], v[42:43], v[174:175], v[20:21] op_sel_hi:[1,0,1]
	v_pk_fma_f32 v[22:23], v[40:41], v[174:175], v[22:23] op_sel_hi:[1,0,1]
	s_waitcnt vmcnt(21) lgkmcnt(11)
	v_pk_fma_f32 v[16:17], v[44:45], v[176:177], v[16:17] op_sel_hi:[1,0,1]
	v_pk_fma_f32 v[18:19], v[46:47], v[176:177], v[18:19] op_sel_hi:[1,0,1]
	s_waitcnt lgkmcnt(10)
	v_pk_fma_f32 v[22:23], v[48:49], v[176:177], v[22:23] op_sel_hi:[1,0,1]
	v_pk_fma_f32 v[20:21], v[50:51], v[176:177], v[20:21] op_sel_hi:[1,0,1]
	s_waitcnt vmcnt(20) lgkmcnt(9)
	v_pk_fma_f32 v[18:19], v[54:55], v[178:179], v[18:19] op_sel_hi:[1,0,1]
	v_pk_fma_f32 v[16:17], v[52:53], v[178:179], v[16:17] op_sel_hi:[1,0,1]
	s_waitcnt lgkmcnt(8)
	v_pk_fma_f32 v[20:21], v[58:59], v[178:179], v[20:21] op_sel_hi:[1,0,1]
	v_pk_fma_f32 v[22:23], v[56:57], v[178:179], v[22:23] op_sel_hi:[1,0,1]
	s_waitcnt vmcnt(19) lgkmcnt(7)
	v_pk_fma_f32 v[16:17], v[60:61], v[180:181], v[16:17] op_sel_hi:[1,0,1]
	v_pk_fma_f32 v[18:19], v[62:63], v[180:181], v[18:19] op_sel_hi:[1,0,1]
	s_waitcnt lgkmcnt(6)
	v_pk_fma_f32 v[22:23], v[64:65], v[180:181], v[22:23] op_sel_hi:[1,0,1]
	v_pk_fma_f32 v[20:21], v[66:67], v[180:181], v[20:21] op_sel_hi:[1,0,1]
	s_waitcnt vmcnt(18) lgkmcnt(5)
	v_pk_fma_f32 v[18:19], v[70:71], v[182:183], v[18:19] op_sel_hi:[1,0,1]
	v_pk_fma_f32 v[16:17], v[68:69], v[182:183], v[16:17] op_sel_hi:[1,0,1]
	s_waitcnt lgkmcnt(4)
	v_pk_fma_f32 v[20:21], v[74:75], v[182:183], v[20:21] op_sel_hi:[1,0,1]
	v_pk_fma_f32 v[22:23], v[72:73], v[182:183], v[22:23] op_sel_hi:[1,0,1]
	s_waitcnt vmcnt(17) lgkmcnt(3)
	v_pk_fma_f32 v[16:17], v[76:77], v[184:185], v[16:17] op_sel_hi:[1,0,1]
	v_pk_fma_f32 v[18:19], v[78:79], v[184:185], v[18:19] op_sel_hi:[1,0,1]
	s_waitcnt lgkmcnt(2)
	v_pk_fma_f32 v[22:23], v[80:81], v[184:185], v[22:23] op_sel_hi:[1,0,1]
	v_pk_fma_f32 v[20:21], v[82:83], v[184:185], v[20:21] op_sel_hi:[1,0,1]
	s_waitcnt vmcnt(16) lgkmcnt(1)
	v_pk_fma_f32 v[18:19], v[86:87], v[186:187], v[18:19] op_sel_hi:[1,0,1]
	v_pk_fma_f32 v[16:17], v[84:85], v[186:187], v[16:17] op_sel_hi:[1,0,1]
	s_waitcnt lgkmcnt(0)
	v_pk_fma_f32 v[20:21], v[90:91], v[186:187], v[20:21] op_sel_hi:[1,0,1]
	v_pk_fma_f32 v[22:23], v[88:89], v[186:187], v[22:23] op_sel_hi:[1,0,1]
	v_add_u32_e32 v7, 0x600, v5
	ds_read_b128 v[26:29], v7
	ds_read_b128 v[32:35], v7 offset:16
	ds_read_b128 v[36:39], v7 offset:32
	ds_read_b128 v[40:43], v7 offset:48
	ds_read_b128 v[44:47], v7 offset:64
	ds_read_b128 v[48:51], v7 offset:80
	ds_read_b128 v[52:55], v7 offset:96
	ds_read_b128 v[56:59], v7 offset:112
	ds_read_b128 v[60:63], v7 offset:128
	ds_read_b128 v[64:67], v7 offset:144
	ds_read_b128 v[68:71], v7 offset:160
	ds_read_b128 v[72:75], v7 offset:176
	ds_read_b128 v[76:79], v7 offset:192
	ds_read_b128 v[80:83], v7 offset:208
	ds_read_b128 v[84:87], v7 offset:224
	ds_read_b128 v[88:91], v7 offset:240
	s_waitcnt vmcnt(15) lgkmcnt(14)
	v_pk_fma_f32 v[16:17], v[26:27], v[188:189], v[16:17] op_sel_hi:[1,0,1]
	v_pk_fma_f32 v[18:19], v[28:29], v[188:189], v[18:19] op_sel_hi:[1,0,1]
	v_pk_fma_f32 v[22:23], v[32:33], v[188:189], v[22:23] op_sel_hi:[1,0,1]
	v_pk_fma_f32 v[20:21], v[34:35], v[188:189], v[20:21] op_sel_hi:[1,0,1]
	s_waitcnt vmcnt(14) lgkmcnt(13)
	v_pk_fma_f32 v[18:19], v[38:39], v[190:191], v[18:19] op_sel_hi:[1,0,1]
	v_pk_fma_f32 v[16:17], v[36:37], v[190:191], v[16:17] op_sel_hi:[1,0,1]
	s_waitcnt lgkmcnt(12)
	v_pk_fma_f32 v[20:21], v[42:43], v[190:191], v[20:21] op_sel_hi:[1,0,1]
	v_pk_fma_f32 v[22:23], v[40:41], v[190:191], v[22:23] op_sel_hi:[1,0,1]
	s_waitcnt vmcnt(13) lgkmcnt(11)
	v_pk_fma_f32 v[16:17], v[44:45], v[192:193], v[16:17] op_sel_hi:[1,0,1]
	v_pk_fma_f32 v[18:19], v[46:47], v[192:193], v[18:19] op_sel_hi:[1,0,1]
	s_waitcnt lgkmcnt(10)
	v_pk_fma_f32 v[22:23], v[48:49], v[192:193], v[22:23] op_sel_hi:[1,0,1]
	v_pk_fma_f32 v[20:21], v[50:51], v[192:193], v[20:21] op_sel_hi:[1,0,1]
	s_waitcnt vmcnt(12) lgkmcnt(9)
	v_pk_fma_f32 v[18:19], v[54:55], v[194:195], v[18:19] op_sel_hi:[1,0,1]
	v_pk_fma_f32 v[16:17], v[52:53], v[194:195], v[16:17] op_sel_hi:[1,0,1]
	s_waitcnt lgkmcnt(8)
	v_pk_fma_f32 v[20:21], v[58:59], v[194:195], v[20:21] op_sel_hi:[1,0,1]
	v_pk_fma_f32 v[22:23], v[56:57], v[194:195], v[22:23] op_sel_hi:[1,0,1]
	s_waitcnt vmcnt(11) lgkmcnt(7)
	v_pk_fma_f32 v[16:17], v[60:61], v[196:197], v[16:17] op_sel_hi:[1,0,1]
	v_pk_fma_f32 v[18:19], v[62:63], v[196:197], v[18:19] op_sel_hi:[1,0,1]
	s_waitcnt lgkmcnt(6)
	v_pk_fma_f32 v[22:23], v[64:65], v[196:197], v[22:23] op_sel_hi:[1,0,1]
	v_pk_fma_f32 v[20:21], v[66:67], v[196:197], v[20:21] op_sel_hi:[1,0,1]
	s_waitcnt vmcnt(10) lgkmcnt(5)
	v_pk_fma_f32 v[18:19], v[70:71], v[198:199], v[18:19] op_sel_hi:[1,0,1]
	v_pk_fma_f32 v[16:17], v[68:69], v[198:199], v[16:17] op_sel_hi:[1,0,1]
	s_waitcnt lgkmcnt(4)
	v_pk_fma_f32 v[20:21], v[74:75], v[198:199], v[20:21] op_sel_hi:[1,0,1]
	v_pk_fma_f32 v[22:23], v[72:73], v[198:199], v[22:23] op_sel_hi:[1,0,1]
	s_waitcnt vmcnt(9) lgkmcnt(3)
	v_pk_fma_f32 v[16:17], v[76:77], v[200:201], v[16:17] op_sel_hi:[1,0,1]
	v_pk_fma_f32 v[18:19], v[78:79], v[200:201], v[18:19] op_sel_hi:[1,0,1]
	s_waitcnt lgkmcnt(2)
	v_pk_fma_f32 v[22:23], v[80:81], v[200:201], v[22:23] op_sel_hi:[1,0,1]
	v_pk_fma_f32 v[20:21], v[82:83], v[200:201], v[20:21] op_sel_hi:[1,0,1]
	s_waitcnt vmcnt(8) lgkmcnt(1)
	v_pk_fma_f32 v[18:19], v[86:87], v[202:203], v[18:19] op_sel_hi:[1,0,1]
	v_pk_fma_f32 v[16:17], v[84:85], v[202:203], v[16:17] op_sel_hi:[1,0,1]
	s_waitcnt lgkmcnt(0)
	v_pk_fma_f32 v[20:21], v[90:91], v[202:203], v[20:21] op_sel_hi:[1,0,1]
	v_pk_fma_f32 v[22:23], v[88:89], v[202:203], v[22:23] op_sel_hi:[1,0,1]
	v_add_u32_e32 v7, 0x700, v5
	ds_read_b128 v[26:29], v7
	ds_read_b128 v[32:35], v7 offset:16
	ds_read_b128 v[36:39], v7 offset:32
	ds_read_b128 v[40:43], v7 offset:48
	ds_read_b128 v[44:47], v7 offset:64
	ds_read_b128 v[48:51], v7 offset:80
	ds_read_b128 v[52:55], v7 offset:96
	ds_read_b128 v[56:59], v7 offset:112
	ds_read_b128 v[60:63], v7 offset:128
	ds_read_b128 v[64:67], v7 offset:144
	ds_read_b128 v[68:71], v7 offset:160
	ds_read_b128 v[72:75], v7 offset:176
	ds_read_b128 v[76:79], v7 offset:192
	ds_read_b128 v[80:83], v7 offset:208
	ds_read_b128 v[84:87], v7 offset:224
	ds_read_b128 v[88:91], v7 offset:240
	s_waitcnt vmcnt(7) lgkmcnt(14)
	v_pk_fma_f32 v[16:17], v[26:27], v[204:205], v[16:17] op_sel_hi:[1,0,1]
	v_pk_fma_f32 v[18:19], v[28:29], v[204:205], v[18:19] op_sel_hi:[1,0,1]
	v_pk_fma_f32 v[22:23], v[32:33], v[204:205], v[22:23] op_sel_hi:[1,0,1]
	v_pk_fma_f32 v[20:21], v[34:35], v[204:205], v[20:21] op_sel_hi:[1,0,1]
	s_waitcnt vmcnt(6) lgkmcnt(13)
	v_pk_fma_f32 v[18:19], v[38:39], v[206:207], v[18:19] op_sel_hi:[1,0,1]
	v_pk_fma_f32 v[16:17], v[36:37], v[206:207], v[16:17] op_sel_hi:[1,0,1]
	s_waitcnt lgkmcnt(12)
	v_pk_fma_f32 v[20:21], v[42:43], v[206:207], v[20:21] op_sel_hi:[1,0,1]
	v_pk_fma_f32 v[22:23], v[40:41], v[206:207], v[22:23] op_sel_hi:[1,0,1]
	s_waitcnt vmcnt(5) lgkmcnt(11)
	v_pk_fma_f32 v[16:17], v[44:45], v[208:209], v[16:17] op_sel_hi:[1,0,1]
	v_pk_fma_f32 v[18:19], v[46:47], v[208:209], v[18:19] op_sel_hi:[1,0,1]
	s_waitcnt lgkmcnt(10)
	v_pk_fma_f32 v[22:23], v[48:49], v[208:209], v[22:23] op_sel_hi:[1,0,1]
	v_pk_fma_f32 v[20:21], v[50:51], v[208:209], v[20:21] op_sel_hi:[1,0,1]
	s_waitcnt vmcnt(4) lgkmcnt(9)
	v_pk_fma_f32 v[18:19], v[54:55], v[210:211], v[18:19] op_sel_hi:[1,0,1]
	v_pk_fma_f32 v[16:17], v[52:53], v[210:211], v[16:17] op_sel_hi:[1,0,1]
	s_waitcnt lgkmcnt(8)
	v_pk_fma_f32 v[20:21], v[58:59], v[210:211], v[20:21] op_sel_hi:[1,0,1]
	v_pk_fma_f32 v[22:23], v[56:57], v[210:211], v[22:23] op_sel_hi:[1,0,1]
	s_waitcnt vmcnt(3) lgkmcnt(7)
	v_pk_fma_f32 v[16:17], v[60:61], v[212:213], v[16:17] op_sel_hi:[1,0,1]
	v_pk_fma_f32 v[18:19], v[62:63], v[212:213], v[18:19] op_sel_hi:[1,0,1]
	s_waitcnt lgkmcnt(6)
	v_pk_fma_f32 v[22:23], v[64:65], v[212:213], v[22:23] op_sel_hi:[1,0,1]
	v_pk_fma_f32 v[20:21], v[66:67], v[212:213], v[20:21] op_sel_hi:[1,0,1]
	s_waitcnt vmcnt(2) lgkmcnt(5)
	v_pk_fma_f32 v[18:19], v[70:71], v[214:215], v[18:19] op_sel_hi:[1,0,1]
	v_pk_fma_f32 v[16:17], v[68:69], v[214:215], v[16:17] op_sel_hi:[1,0,1]
	s_waitcnt lgkmcnt(4)
	v_pk_fma_f32 v[20:21], v[74:75], v[214:215], v[20:21] op_sel_hi:[1,0,1]
	v_pk_fma_f32 v[22:23], v[72:73], v[214:215], v[22:23] op_sel_hi:[1,0,1]
	s_waitcnt vmcnt(1) lgkmcnt(3)
	v_pk_fma_f32 v[16:17], v[76:77], v[216:217], v[16:17] op_sel_hi:[1,0,1]
	v_pk_fma_f32 v[18:19], v[78:79], v[216:217], v[18:19] op_sel_hi:[1,0,1]
	s_waitcnt lgkmcnt(2)
	v_pk_fma_f32 v[22:23], v[80:81], v[216:217], v[22:23] op_sel_hi:[1,0,1]
	v_pk_fma_f32 v[20:21], v[82:83], v[216:217], v[20:21] op_sel_hi:[1,0,1]
	s_waitcnt vmcnt(0) lgkmcnt(1)
	v_pk_fma_f32 v[18:19], v[86:87], v[218:219], v[18:19] op_sel_hi:[1,0,1]
	v_pk_fma_f32 v[16:17], v[84:85], v[218:219], v[16:17] op_sel_hi:[1,0,1]
	s_waitcnt lgkmcnt(0)
	v_pk_fma_f32 v[20:21], v[90:91], v[218:219], v[20:21] op_sel_hi:[1,0,1]
	v_pk_fma_f32 v[22:23], v[88:89], v[218:219], v[22:23] op_sel_hi:[1,0,1]
	s_movk_i32 s7, 0x800
	v_add_u32_e32 v7, 0x8000, v1
	ds_write2_b32 v7, v16, v17 offset1:32
	ds_write2_b32 v7, v22, v23 offset0:128 offset1:160
	ds_write2_b32 v7, v18, v19 offset0:64 offset1:96
	ds_write2_b32 v7, v20, v21 offset0:192 offset1:224
	s_waitcnt lgkmcnt(0)
	s_barrier
	s_and_saveexec_b64 s[12:13], s[0:1]
	s_cbranch_execz .LBB0_8
	v_add_u32_e32 v14, s4, v4
	v_ashrrev_i32_e32 v15, 31, v14
	v_lshl_add_u64 v[14:15], v[14:15], 2, s[10:11]
	global_load_dword v7, v[14:15], off
	ds_read2st64_b32 v[14:15], v3 offset0:128 offset1:132
	ds_read2st64_b32 v[16:17], v3 offset0:136 offset1:140
	ds_read2st64_b32 v[18:19], v3 offset0:144 offset1:148
	ds_read2st64_b32 v[20:21], v3 offset0:152 offset1:156
	ds_read2st64_b32 v[22:23], v3 offset0:160 offset1:164
	ds_read2st64_b32 v[26:27], v3 offset0:168 offset1:172
	ds_read2st64_b32 v[28:29], v3 offset0:176 offset1:180
	ds_read2st64_b32 v[32:33], v3 offset0:184 offset1:188
	v_mad_i64_i32 v[34:35], s[6:7], s6, v6, 0
	v_lshl_add_u64 v[34:35], v[34:35], 2, s[8:9]
	v_lshlrev_b32_e32 v8, 2, v4
	v_lshl_add_u64 v[34:35], s[4:5], 2, v[34:35]
	s_waitcnt vmcnt(0) lgkmcnt(7)
	v_add_f32_e32 v7, v7, v14
	v_add_f32_e32 v7, v7, v15
	s_waitcnt lgkmcnt(6)
	v_add_f32_e32 v7, v7, v16
	v_add_f32_e32 v7, v7, v17
	s_waitcnt lgkmcnt(5)
	v_add_f32_e32 v7, v7, v18
	v_add_f32_e32 v7, v7, v19
	s_waitcnt lgkmcnt(4)
	v_add_f32_e32 v7, v7, v20
	v_add_f32_e32 v7, v7, v21
	s_waitcnt lgkmcnt(3)
	v_add_f32_e32 v7, v7, v22
	v_add_f32_e32 v7, v7, v23
	s_waitcnt lgkmcnt(2)
	v_add_f32_e32 v7, v7, v26
	v_add_f32_e32 v7, v7, v27
	s_waitcnt lgkmcnt(1)
	v_add_f32_e32 v7, v7, v28
	v_add_f32_e32 v7, v7, v29
	s_waitcnt lgkmcnt(0)
	v_add_f32_e32 v7, v7, v32
	v_add_f32_e32 v7, v7, v33
	v_lshl_add_u64 v[14:15], v[34:35], 0, v[8:9]
	global_store_dword v[14:15], v7, off
	s_branch .LBB0_8
